# stack2 plus GEMM accumulators cleared with 64-bit moves
# baseline (speedup 1.0000x reference)
; template <class Epi, bool SP2 = true, bool ALIGN_EPI = true>
; __device__ __forceinline__ void gemm_phase(LAS unsigned char* lds, const Gemm g, const StaticOrder& S, const Epi& E, const int tid) {
;     ...
;         const bool has_next = S.next(ui + 1, nxt);
;         const char* nA = has_next ? (const char*)g.A + (size_t)nxt.pm * tstep : cA; const char* nB = has_next ? (const char*)g.Bt + (size_t)nxt.pn * tstep : cB;
;     ...
; #pragma unroll
;         for (int a = 0; a < 2; ++a)
; #pragma unroll
;             for (int b = 0; b < 2; ++b)
; #pragma unroll
;                 for (int m = 0; m < 4; ++m)
; #pragma unroll
;                     for (int n = 0; n < 2; ++n) acc[a][b][m][n] = (f32x4){0.f, 0.f, 0.f, 0.f};
;         cur = nxt; cA = nA; cB = nB; ++ui;
.LBB0_134:
	s_ashr_i32 s49, s48, 31
	s_lshl_b64 s[24:25], s[48:49], 20
	s_add_u32 s52, s90, s24
	s_addc_u32 s53, s91, s25
	s_and_b64 s[24:25], s[42:43], exec
	s_cselect_b32 s49, s53, s19
	s_cselect_b32 s95, s52, s18
	s_ashr_i32 s47, s46, 31
	s_lshl_b64 s[24:25], s[46:47], 20
	v_readlane_b32 s12, v250, 30
	s_add_u32 s54, s12, s24
	v_readlane_b32 s12, v250, 31
	s_addc_u32 s55, s12, s25
	s_and_b64 s[24:25], s[42:43], exec
	s_cselect_b32 s78, s55, s29
	s_cselect_b32 s73, s54, s28
	s_lshl_b32 s47, s40, 8
	s_lshl_b32 s12, s20, 8
	s_add_i32 s47, s47, s6
	s_or_b32 s69, s12, s23
	s_add_u32 s24, s18, 0x100
	s_addc_u32 s25, s19, 0
	s_add_u32 s44, s28, 0x100
	s_addc_u32 s45, s29, 0
	s_add_u32 s18, s18, 0x80080
	s_addc_u32 s19, s19, 0
	v_mov_b32_e32 v0, 0
	v_mov_b32_e32 v1, 0
	v_mov_b64_e32 v[2:3], 0
	v_mov_b64_e32 v[4:5], 0
	v_mov_b64_e32 v[6:7], 0
	v_mov_b64_e32 v[8:9], 0
	v_mov_b64_e32 v[10:11], 0
	v_mov_b64_e32 v[12:13], 0
	v_mov_b64_e32 v[14:15], 0
	v_mov_b64_e32 v[16:17], 0
	v_mov_b64_e32 v[18:19], 0
	v_mov_b64_e32 v[20:21], 0
	v_mov_b64_e32 v[22:23], 0
	v_mov_b64_e32 v[24:25], 0
	v_mov_b64_e32 v[26:27], 0
	v_mov_b64_e32 v[28:29], 0
	v_mov_b64_e32 v[30:31], 0
	v_mov_b64_e32 v[32:33], 0
	v_mov_b64_e32 v[34:35], 0
	v_mov_b64_e32 v[36:37], 0
	v_mov_b64_e32 v[38:39], 0
	v_mov_b64_e32 v[40:41], 0
	v_mov_b64_e32 v[42:43], 0
	v_mov_b64_e32 v[44:45], 0
	v_mov_b64_e32 v[46:47], 0
	v_mov_b64_e32 v[48:49], 0
	v_mov_b64_e32 v[50:51], 0
	v_mov_b64_e32 v[52:53], 0
	v_mov_b64_e32 v[54:55], 0
	v_mov_b64_e32 v[56:57], 0
	v_mov_b64_e32 v[58:59], 0
	v_mov_b64_e32 v[60:61], 0
	v_mov_b64_e32 v[62:63], 0
	v_mov_b64_e32 v[64:65], 0
	v_mov_b64_e32 v[66:67], 0
	v_mov_b64_e32 v[68:69], 0
	v_mov_b64_e32 v[70:71], 0
	v_mov_b64_e32 v[72:73], 0
	v_mov_b64_e32 v[74:75], 0
	v_mov_b64_e32 v[76:77], 0
	v_mov_b64_e32 v[78:79], 0
	v_mov_b64_e32 v[80:81], 0
	v_mov_b64_e32 v[82:83], 0
	v_mov_b64_e32 v[84:85], 0
	v_mov_b64_e32 v[86:87], 0
	v_mov_b64_e32 v[88:89], 0
	v_mov_b64_e32 v[90:91], 0
	v_mov_b64_e32 v[92:93], 0
	v_mov_b64_e32 v[94:95], 0
	v_mov_b64_e32 v[96:97], 0
	v_mov_b64_e32 v[98:99], 0
	v_mov_b64_e32 v[100:101], 0
	v_mov_b64_e32 v[102:103], 0
	v_mov_b64_e32 v[104:105], 0
	v_mov_b64_e32 v[106:107], 0
	v_mov_b64_e32 v[108:109], 0
	v_mov_b64_e32 v[110:111], 0
	v_mov_b64_e32 v[112:113], 0
	v_mov_b64_e32 v[114:115], 0
	v_mov_b64_e32 v[116:117], 0
	v_mov_b64_e32 v[118:119], 0
	v_mov_b64_e32 v[120:121], 0
	v_mov_b64_e32 v[122:123], 0
	v_mov_b64_e32 v[124:125], 0
	v_mov_b64_e32 v[126:127], 0
	s_mov_b64 s[50:51], 0x8000
	v_lshl_add_u64 v[216:217], s[18:19], 0, v[212:213]
	v_lshl_add_u64 v[218:219], s[18:19], 0, v[214:215]
	s_mov_b32 s20, 0
	s_mov_b64 s[40:41], -1
	s_mov_b64 s[56:57], 0

; template <class Epi, bool SP2 = true, bool ALIGN_EPI = true>
; __device__ __forceinline__ void gemm_phase(LAS unsigned char* lds, const Gemm g, const StaticOrder& S, const Epi& E, const int tid) {
;     ...
;         const bool has_next = S.next(ui + 1, nxt);
;         const char* nA = has_next ? (const char*)g.A + (size_t)nxt.pm * tstep : cA; const char* nB = has_next ? (const char*)g.Bt + (size_t)nxt.pn * tstep : cB;
;     ...
; #pragma unroll
;         for (int a = 0; a < 2; ++a)
; #pragma unroll
;             for (int b = 0; b < 2; ++b)
; #pragma unroll
;                 for (int m = 0; m < 4; ++m)
; #pragma unroll
;                     for (int n = 0; n < 2; ++n) acc[a][b][m][n] = (f32x4){0.f, 0.f, 0.f, 0.f};
;         cur = nxt; cA = nA; cB = nB; ++ui;
.LBB0_166:
	s_ashr_i32 s93, s92, 31
	s_lshl_b64 s[28:29], s[92:93], 19
	v_readlane_b32 s0, v251, 4
	s_add_u32 s40, s0, s28
	s_addc_u32 s41, s68, s29
	s_and_b64 s[28:29], s[42:43], exec
	s_cselect_b32 s45, s41, s25
	s_cselect_b32 s46, s40, s24
	s_ashr_i32 s59, s58, 31
	s_lshl_b64 s[28:29], s[58:59], 19
	v_readlane_b32 s12, v249, 13
	s_add_u32 s52, s12, s28
	v_readlane_b32 s12, v249, 14
	s_addc_u32 s53, s12, s29
	s_and_b64 s[28:29], s[42:43], exec
	s_cselect_b32 s47, s53, s19
	s_cselect_b32 s48, s52, s18
	s_add_u32 s24, s24, 0x40080
	s_addc_u32 s25, s25, 0
	s_add_u32 s49, s18, 0x100
	v_mov_b32_e32 v0, 0
	v_mov_b32_e32 v1, 0
	v_mov_b64_e32 v[2:3], 0
	v_mov_b64_e32 v[4:5], 0
	v_mov_b64_e32 v[6:7], 0
	v_mov_b64_e32 v[8:9], 0
	v_mov_b64_e32 v[10:11], 0
	v_mov_b64_e32 v[12:13], 0
	v_mov_b64_e32 v[14:15], 0
	v_mov_b64_e32 v[16:17], 0
	v_mov_b64_e32 v[18:19], 0
	v_mov_b64_e32 v[20:21], 0
	v_mov_b64_e32 v[22:23], 0
	v_mov_b64_e32 v[24:25], 0
	v_mov_b64_e32 v[26:27], 0
	v_mov_b64_e32 v[28:29], 0
	v_mov_b64_e32 v[30:31], 0
	v_mov_b64_e32 v[32:33], 0
	v_mov_b64_e32 v[34:35], 0
	v_mov_b64_e32 v[36:37], 0
	v_mov_b64_e32 v[38:39], 0
	v_mov_b64_e32 v[40:41], 0
	v_mov_b64_e32 v[42:43], 0
	v_mov_b64_e32 v[44:45], 0
	v_mov_b64_e32 v[46:47], 0
	v_mov_b64_e32 v[48:49], 0
	v_mov_b64_e32 v[50:51], 0
	v_mov_b64_e32 v[52:53], 0
	v_mov_b64_e32 v[54:55], 0
	v_mov_b64_e32 v[56:57], 0
	v_mov_b64_e32 v[58:59], 0
	v_mov_b64_e32 v[60:61], 0
	v_mov_b64_e32 v[62:63], 0
	v_mov_b64_e32 v[64:65], 0
	v_mov_b64_e32 v[66:67], 0
	v_mov_b64_e32 v[68:69], 0
	v_mov_b64_e32 v[70:71], 0
	v_mov_b64_e32 v[72:73], 0
	v_mov_b64_e32 v[74:75], 0
	v_mov_b64_e32 v[76:77], 0
	v_mov_b64_e32 v[78:79], 0
	v_mov_b64_e32 v[80:81], 0
	v_mov_b64_e32 v[82:83], 0
	v_mov_b64_e32 v[84:85], 0
	v_mov_b64_e32 v[86:87], 0
	v_mov_b64_e32 v[88:89], 0
	v_mov_b64_e32 v[90:91], 0
	v_mov_b64_e32 v[92:93], 0
	v_mov_b64_e32 v[94:95], 0
	v_mov_b64_e32 v[96:97], 0
	v_mov_b64_e32 v[98:99], 0
	v_mov_b64_e32 v[100:101], 0
	v_mov_b64_e32 v[102:103], 0
	v_mov_b64_e32 v[104:105], 0
	v_mov_b64_e32 v[106:107], 0
	v_mov_b64_e32 v[108:109], 0
	v_mov_b64_e32 v[110:111], 0
	v_mov_b64_e32 v[112:113], 0
	v_mov_b64_e32 v[114:115], 0
	v_mov_b64_e32 v[116:117], 0
	v_mov_b64_e32 v[118:119], 0
	v_mov_b64_e32 v[120:121], 0
	v_mov_b64_e32 v[122:123], 0
	v_mov_b64_e32 v[124:125], 0
	v_mov_b64_e32 v[126:127], 0
	s_addc_u32 s54, s19, 0
	s_mov_b32 s55, -2

; template <class Epi, bool SP2 = true, bool ALIGN_EPI = true>
; __device__ __forceinline__ void gemm_phase(LAS unsigned char* lds, const Gemm g, const StaticOrder& S, const Epi& E, const int tid) {
;     ...
;         const bool has_next = S.next(ui + 1, nxt);
;         const char* nA = has_next ? (const char*)g.A + (size_t)nxt.pm * tstep : cA; const char* nB = has_next ? (const char*)g.Bt + (size_t)nxt.pn * tstep : cB;
;     ...
; #pragma unroll
;         for (int a = 0; a < 2; ++a)
; #pragma unroll
;             for (int b = 0; b < 2; ++b)
; #pragma unroll
;                 for (int m = 0; m < 4; ++m)
; #pragma unroll
;                     for (int n = 0; n < 2; ++n) acc[a][b][m][n] = (f32x4){0.f, 0.f, 0.f, 0.f};
;         cur = nxt; cA = nA; cB = nB; ++ui;
.LBB0_324:
	s_ashr_i32 s59, s58, 31
	s_lshl_b64 s[12:13], s[58:59], 19
	v_readlane_b32 s28, v249, 31
	v_readlane_b32 s29, v249, 32
	s_add_u32 s56, s28, s12
	s_addc_u32 s57, s29, s13
	s_and_b64 s[12:13], s[42:43], exec
	s_cselect_b32 s59, s57, s25
	s_cselect_b32 s78, s56, s24
	s_ashr_i32 s55, s54, 31
	s_lshl_b64 s[12:13], s[54:55], 19
	v_readlane_b32 s22, v249, 27
	s_add_u32 s92, s22, s12
	v_readlane_b32 s12, v249, 28
	s_addc_u32 s93, s12, s13
	s_and_b64 s[12:13], s[42:43], exec
	s_cselect_b32 s55, s93, s19
	s_cselect_b32 s80, s92, s18
	s_add_u32 s95, s18, 0x100
	v_mov_b32_e32 v0, 0
	v_mov_b32_e32 v1, 0
	v_mov_b64_e32 v[2:3], 0
	v_mov_b64_e32 v[4:5], 0
	v_mov_b64_e32 v[6:7], 0
	v_mov_b64_e32 v[8:9], 0
	v_mov_b64_e32 v[10:11], 0
	v_mov_b64_e32 v[12:13], 0
	v_mov_b64_e32 v[14:15], 0
	v_mov_b64_e32 v[16:17], 0
	v_mov_b64_e32 v[18:19], 0
	v_mov_b64_e32 v[20:21], 0
	v_mov_b64_e32 v[22:23], 0
	v_mov_b64_e32 v[24:25], 0
	v_mov_b64_e32 v[26:27], 0
	v_mov_b64_e32 v[28:29], 0
	v_mov_b64_e32 v[30:31], 0
	v_mov_b64_e32 v[32:33], 0
	v_mov_b64_e32 v[34:35], 0
	v_mov_b64_e32 v[36:37], 0
	v_mov_b64_e32 v[38:39], 0
	v_mov_b64_e32 v[40:41], 0
	v_mov_b64_e32 v[42:43], 0
	v_mov_b64_e32 v[44:45], 0
	v_mov_b64_e32 v[46:47], 0
	v_mov_b64_e32 v[48:49], 0
	v_mov_b64_e32 v[50:51], 0
	v_mov_b64_e32 v[52:53], 0
	v_mov_b64_e32 v[54:55], 0
	v_mov_b64_e32 v[56:57], 0
	v_mov_b64_e32 v[58:59], 0
	v_mov_b64_e32 v[60:61], 0
	v_mov_b64_e32 v[62:63], 0
	v_mov_b64_e32 v[64:65], 0
	v_mov_b64_e32 v[66:67], 0
	v_mov_b64_e32 v[68:69], 0
	v_mov_b64_e32 v[70:71], 0
	v_mov_b64_e32 v[72:73], 0
	v_mov_b64_e32 v[74:75], 0
	v_mov_b64_e32 v[76:77], 0
	v_mov_b64_e32 v[78:79], 0
	v_mov_b64_e32 v[80:81], 0
	v_mov_b64_e32 v[82:83], 0
	v_mov_b64_e32 v[84:85], 0
	v_mov_b64_e32 v[86:87], 0
	v_mov_b64_e32 v[88:89], 0
	v_mov_b64_e32 v[90:91], 0
	v_mov_b64_e32 v[92:93], 0
	v_mov_b64_e32 v[94:95], 0
	v_mov_b64_e32 v[96:97], 0
	v_mov_b64_e32 v[98:99], 0
	v_mov_b64_e32 v[100:101], 0
	v_mov_b64_e32 v[102:103], 0
	v_mov_b64_e32 v[104:105], 0
	v_mov_b64_e32 v[106:107], 0
	v_mov_b64_e32 v[108:109], 0
	v_mov_b64_e32 v[110:111], 0
	v_mov_b64_e32 v[112:113], 0
	v_mov_b64_e32 v[114:115], 0
	v_mov_b64_e32 v[116:117], 0
	v_mov_b64_e32 v[118:119], 0
	v_mov_b64_e32 v[120:121], 0
	v_mov_b64_e32 v[122:123], 0
	v_mov_b64_e32 v[124:125], 0
	v_mov_b64_e32 v[126:127], 0
	s_addc_u32 vcc_lo, s19, 0
	s_mov_b32 vcc_hi, -2

; template <class Epi, bool SP2 = true, bool ALIGN_EPI = true>
; __device__ __forceinline__ void gemm_phase(LAS unsigned char* lds, const Gemm g, const StaticOrder& S, const Epi& E, const int tid) {
;     ...
; #pragma unroll
;         for (int a = 0; a < 2; ++a)
; #pragma unroll
;             for (int b = 0; b < 2; ++b)
; #pragma unroll
;                 for (int m = 0; m < 4; ++m)
; #pragma unroll
;                     for (int n = 0; n < 2; ++n) acc[a][b][m][n] = (f32x4){0.f, 0.f, 0.f, 0.f};
;         cur = nxt; cA = nA; cB = nB; ++ui;
.LBB0_448:
	s_add_u32 s80, s18, 0x100
	v_mov_b32_e32 v0, 0
	v_mov_b32_e32 v1, 0
	v_mov_b64_e32 v[2:3], 0
	v_mov_b64_e32 v[4:5], 0
	v_mov_b64_e32 v[6:7], 0
	v_mov_b64_e32 v[8:9], 0
	v_mov_b64_e32 v[10:11], 0
	v_mov_b64_e32 v[12:13], 0
	v_mov_b64_e32 v[14:15], 0
	v_mov_b64_e32 v[16:17], 0
	v_mov_b64_e32 v[18:19], 0
	v_mov_b64_e32 v[20:21], 0
	v_mov_b64_e32 v[22:23], 0
	v_mov_b64_e32 v[24:25], 0
	v_mov_b64_e32 v[26:27], 0
	v_mov_b64_e32 v[28:29], 0
	v_mov_b64_e32 v[30:31], 0
	v_mov_b64_e32 v[32:33], 0
	v_mov_b64_e32 v[34:35], 0
	v_mov_b64_e32 v[36:37], 0
	v_mov_b64_e32 v[38:39], 0
	v_mov_b64_e32 v[40:41], 0
	v_mov_b64_e32 v[42:43], 0
	v_mov_b64_e32 v[44:45], 0
	v_mov_b64_e32 v[46:47], 0
	v_mov_b64_e32 v[48:49], 0
	v_mov_b64_e32 v[50:51], 0
	v_mov_b64_e32 v[52:53], 0
	v_mov_b64_e32 v[54:55], 0
	v_mov_b64_e32 v[56:57], 0
	v_mov_b64_e32 v[58:59], 0
	v_mov_b64_e32 v[60:61], 0
	v_mov_b64_e32 v[62:63], 0
	v_mov_b64_e32 v[64:65], 0
	v_mov_b64_e32 v[66:67], 0
	v_mov_b64_e32 v[68:69], 0
	v_mov_b64_e32 v[70:71], 0
	v_mov_b64_e32 v[72:73], 0
	v_mov_b64_e32 v[74:75], 0
	v_mov_b64_e32 v[76:77], 0
	v_mov_b64_e32 v[78:79], 0
	v_mov_b64_e32 v[80:81], 0
	v_mov_b64_e32 v[82:83], 0
	v_mov_b64_e32 v[84:85], 0
	v_mov_b64_e32 v[86:87], 0
	v_mov_b64_e32 v[88:89], 0
	v_mov_b64_e32 v[90:91], 0
	v_mov_b64_e32 v[92:93], 0
	v_mov_b64_e32 v[94:95], 0
	v_mov_b64_e32 v[96:97], 0
	v_mov_b64_e32 v[98:99], 0
	v_mov_b64_e32 v[100:101], 0
	v_mov_b64_e32 v[102:103], 0
	v_mov_b64_e32 v[104:105], 0
	v_mov_b64_e32 v[106:107], 0
	v_mov_b64_e32 v[108:109], 0
	v_mov_b64_e32 v[110:111], 0
	v_mov_b64_e32 v[112:113], 0
	v_mov_b64_e32 v[114:115], 0
	v_mov_b64_e32 v[116:117], 0
	v_mov_b64_e32 v[118:119], 0
	v_mov_b64_e32 v[120:121], 0
	v_mov_b64_e32 v[122:123], 0
	v_mov_b64_e32 v[124:125], 0
	v_mov_b64_e32 v[126:127], 0
	s_addc_u32 s95, s19, 0
	s_mov_b32 vcc_lo, -2

; template <class Epi, bool SP2 = true, bool ALIGN_EPI = true>
; __device__ __forceinline__ void gemm_phase(LAS unsigned char* lds, const Gemm g, const StaticOrder& S, const Epi& E, const int tid) {
;     ...
;         const bool has_next = S.next(ui + 1, nxt);
;         const char* nA = has_next ? (const char*)g.A + (size_t)nxt.pm * tstep : cA; const char* nB = has_next ? (const char*)g.Bt + (size_t)nxt.pn * tstep : cB;
;     ...
; #pragma unroll
;         for (int a = 0; a < 2; ++a)
; #pragma unroll
;             for (int b = 0; b < 2; ++b)
; #pragma unroll
;                 for (int m = 0; m < 4; ++m)
; #pragma unroll
;                     for (int n = 0; n < 2; ++n) acc[a][b][m][n] = (f32x4){0.f, 0.f, 0.f, 0.f};
;         cur = nxt; cA = nA; cB = nB; ++ui;
.LBB0_513:
	s_ashr_i32 s49, s48, 31
	s_lshl_b64 s[28:29], s[48:49], 19
	v_readlane_b32 s0, v251, 4
	s_add_u32 s52, s0, s28
	s_addc_u32 s53, s68, s29
	s_and_b64 s[28:29], s[42:43], exec
	s_cselect_b32 s49, s53, s25
	s_cselect_b32 s72, s52, s24
	s_ashr_i32 s47, s46, 31
	s_lshl_b64 s[28:29], s[46:47], 19
	v_readlane_b32 s0, v250, 46
	v_readlane_b32 s1, v250, 47
	s_add_u32 s54, s0, s28
	s_addc_u32 s55, s1, s29
	s_and_b64 s[28:29], s[42:43], exec
	s_cselect_b32 s47, s55, s19
	s_cselect_b32 s73, s54, s18
	s_add_u32 s24, s24, 0x40080
	s_addc_u32 s25, s25, 0
	s_add_u32 s74, s18, 0x100
	v_mov_b32_e32 v0, 0
	v_mov_b32_e32 v1, 0
	v_mov_b64_e32 v[2:3], 0
	v_mov_b64_e32 v[4:5], 0
	v_mov_b64_e32 v[6:7], 0
	v_mov_b64_e32 v[8:9], 0
	v_mov_b64_e32 v[10:11], 0
	v_mov_b64_e32 v[12:13], 0
	v_mov_b64_e32 v[14:15], 0
	v_mov_b64_e32 v[16:17], 0
	v_mov_b64_e32 v[18:19], 0
	v_mov_b64_e32 v[20:21], 0
	v_mov_b64_e32 v[22:23], 0
	v_mov_b64_e32 v[24:25], 0
	v_mov_b64_e32 v[26:27], 0
	v_mov_b64_e32 v[28:29], 0
	v_mov_b64_e32 v[30:31], 0
	v_mov_b64_e32 v[32:33], 0
	v_mov_b64_e32 v[34:35], 0
	v_mov_b64_e32 v[36:37], 0
	v_mov_b64_e32 v[38:39], 0
	v_mov_b64_e32 v[40:41], 0
	v_mov_b64_e32 v[42:43], 0
	v_mov_b64_e32 v[44:45], 0
	v_mov_b64_e32 v[46:47], 0
	v_mov_b64_e32 v[48:49], 0
	v_mov_b64_e32 v[50:51], 0
	v_mov_b64_e32 v[52:53], 0
	v_mov_b64_e32 v[54:55], 0
	v_mov_b64_e32 v[56:57], 0
	v_mov_b64_e32 v[58:59], 0
	v_mov_b64_e32 v[60:61], 0
	v_mov_b64_e32 v[62:63], 0
	v_mov_b64_e32 v[64:65], 0
	v_mov_b64_e32 v[66:67], 0
	v_mov_b64_e32 v[68:69], 0
	v_mov_b64_e32 v[70:71], 0
	v_mov_b64_e32 v[72:73], 0
	v_mov_b64_e32 v[74:75], 0
	v_mov_b64_e32 v[76:77], 0
	v_mov_b64_e32 v[78:79], 0
	v_mov_b64_e32 v[80:81], 0
	v_mov_b64_e32 v[82:83], 0
	v_mov_b64_e32 v[84:85], 0
	v_mov_b64_e32 v[86:87], 0
	v_mov_b64_e32 v[88:89], 0
	v_mov_b64_e32 v[90:91], 0
	v_mov_b64_e32 v[92:93], 0
	v_mov_b64_e32 v[94:95], 0
	v_mov_b64_e32 v[96:97], 0
	v_mov_b64_e32 v[98:99], 0
	v_mov_b64_e32 v[100:101], 0
	v_mov_b64_e32 v[102:103], 0
	v_mov_b64_e32 v[104:105], 0
	v_mov_b64_e32 v[106:107], 0
	v_mov_b64_e32 v[108:109], 0
	v_mov_b64_e32 v[110:111], 0
	v_mov_b64_e32 v[112:113], 0
	v_mov_b64_e32 v[114:115], 0
	v_mov_b64_e32 v[116:117], 0
	v_mov_b64_e32 v[118:119], 0
	v_mov_b64_e32 v[120:121], 0
	v_mov_b64_e32 v[122:123], 0
	v_mov_b64_e32 v[124:125], 0
	v_mov_b64_e32 v[126:127], 0
	s_addc_u32 s75, s19, 0
	s_mov_b32 s76, -2
